# residual stream (fp16 XB) loads and stores in the residual-GEMM epilogue use the default cache policy instead of nt
# baseline (speedup 1.0000x reference)
;     __device__ __forceinline__ void operator()(const f32x4 (&acc)[2][2][4][2], const Unit& u, int wr, int wc, int fr, int fq, int tid, const Pre& pre) const {
;         const int row0 = u.pm * BM + wr * 64 + fr; const int col0 = u.pn * BM + wc * 32 + 8 * fq;
;         const bool nx = (XT != nullptr);
;         u32x4 bw[4][2][2];
;     ...
;         RES_LOAD(0);
;         LAS float* tb = scr + 1024;
;         if (tid < 256) { tb[tid] = pre.gv; tb[256 + tid] = pre.gsn; }
;         asm volatile("s_waitcnt lgkmcnt(0)" ::: "memory"); __builtin_amdgcn_s_barrier(); asm volatile("" ::: "memory");
;         f32x4 gv[2][2], gsn[2][2];
; #pragma unroll
;         for (int bj = 0; bj < 2; ++bj)
; #pragma unroll
;             for (int n = 0; n < 2; ++n) { gv[bj][n] = *(const LAS f32x4*)(tb + bj * HALF + wc * 32 + 8 * fq + 4 * n); gsn[bj][n] = *(const LAS f32x4*)(tb + 256 + bj * HALF + wc * 32 + 8 * fq + 4 * n); }
;         RES_LOAD(1);
; #pragma unroll
;         for (int q = 0; q < 4; ++q) {
;             const int ai = q >> 1;
; #pragma unroll
;             for (int mm = 0; mm < 2; ++mm) { const int m = (q & 1) * 2 + mm; const size_t off = (size_t)(row0 + ai * HALF + m * 16) * DM + col0; float ss = 0.f;
; #pragma unroll
;                 for (int bj = 0; bj < 2; ++bj) {
;                     const f32x2_t h0 = unpk_h(bw[q][mm][bj].x), h1 = unpk_h(bw[q][mm][bj].y), h2 = unpk_h(bw[q][mm][bj].z), h3 = unpk_h(bw[q][mm][bj].w);
;                     const f32x4 b0 = {h0[0], h0[1], h1[0], h1[1]}, b1 = {h2[0], h2[1], h3[0], h3[1]};
;                     const f32x4 o0 = b0 + gv[bj][0] * acc[ai][bj][m][0], o1 = b1 + gv[bj][1] * acc[ai][bj][m][1];
;                     if (nx) { ss += ((o0[0] * o0[0] + o0[1] * o0[1]) + (o0[2] * o0[2] + o0[3] * o0[3])) + ((o1[0] * o1[0] + o1[1] * o1[1]) + (o1[2] * o1[2] + o1[3] * o1[3]));
;                         u32x4 xw; xw.x = cvtpk_h(o0[0], o0[1]); xw.y = cvtpk_h(o0[2], o0[3]); xw.z = cvtpk_h(o1[0], o1[1]); xw.w = cvtpk_h(o1[2], o1[3]);
;                         __builtin_nontemporal_store(xw, (u32x4*)(xb + off + bj * HALF));
;                         const f32x4 t0 = o0 * gsn[bj][0], t1 = o1 * gsn[bj][1];
;                         u32x4 w; w.x = cvtpk(t0[0], t0[1]); w.y = cvtpk(t0[2], t0[3]); w.z = cvtpk(t1[0], t1[1]); w.w = cvtpk(t1[2], t1[3]);
;                         *(u32x4*)(XT + off + bj * HALF) = w; }
.LBB0_570:
	s_lshl_b32 s60, s60, 8
	v_add_u32_e32 v212, s60, v231
	v_lshl_or_b32 v210, s66, 8, v239
	v_ashrrev_i32_e32 v211, 31, v210
	v_ashrrev_i32_e32 v213, 31, v212
	v_lshl_add_u64 v[208:209], v[210:211], 1, s[42:43]
	v_lshlrev_b64 v[58:59], 11, v[212:213]
	v_or_b32_e32 v218, 16, v212
	v_lshl_add_u64 v[58:59], v[208:209], 0, v[58:59]
	v_ashrrev_i32_e32 v219, 31, v218
	global_load_dwordx4 v[188:191], v[58:59], off
	global_load_dwordx4 v[184:187], v[58:59], off offset:256
	v_lshlrev_b64 v[58:59], 11, v[218:219]
	v_lshl_add_u64 v[58:59], v[208:209], 0, v[58:59]
	global_load_dwordx4 v[180:183], v[58:59], off
	global_load_dwordx4 v[176:179], v[58:59], off offset:256
	s_and_saveexec_b64 s[74:75], s[10:11]
	ds_write2st64_b32 v233, v57, v56 offset1:4
	s_or_b64 exec, exec, s[74:75]
	v_or_b32_e32 v216, 32, v212
	v_ashrrev_i32_e32 v217, 31, v216
	v_lshlrev_b64 v[56:57], 11, v[216:217]
	v_or_b32_e32 v214, 48, v212
	s_waitcnt lgkmcnt(0)
	s_barrier
	v_lshl_add_u64 v[56:57], v[208:209], 0, v[56:57]
	v_ashrrev_i32_e32 v215, 31, v214
	global_load_dwordx4 v[172:175], v[56:57], off
	global_load_dwordx4 v[168:171], v[56:57], off offset:256
	v_lshlrev_b64 v[56:57], 11, v[214:215]
	v_lshl_add_u64 v[56:57], v[208:209], 0, v[56:57]
	global_load_dwordx4 v[164:167], v[56:57], off
	global_load_dwordx4 v[152:155], v[56:57], off offset:256
	s_waitcnt vmcnt(0)
	v_cvt_f32_f16_sdwa v227, v188 dst_sel:DWORD dst_unused:UNUSED_PAD src0_sel:WORD_1
	v_cvt_f32_f16_e32 v226, v188
	v_cvt_f32_f16_sdwa v243, v189 dst_sel:DWORD dst_unused:UNUSED_PAD src0_sel:WORD_1
	v_cvt_f32_f16_e32 v242, v189
	v_cvt_f32_f16_sdwa v189, v190 dst_sel:DWORD dst_unused:UNUSED_PAD src0_sel:WORD_1
	v_cvt_f32_f16_sdwa v245, v191 dst_sel:DWORD dst_unused:UNUSED_PAD src0_sel:WORD_1
	v_cvt_f32_f16_e32 v244, v191
	v_cvt_f32_f16_e32 v188, v190
	ds_read_b128 v[92:95], v234
	ds_read_b128 v[88:91], v234 offset:16
	ds_read_b128 v[84:87], v235
	ds_read_b128 v[80:83], v235 offset:16
	ds_read_b128 v[68:71], v234 offset:512
	ds_read_b128 v[64:67], v234 offset:528
	ds_read_b128 v[60:63], v235 offset:512
	ds_read_b128 v[56:59], v235 offset:528
	v_lshlrev_b64 v[224:225], 10, v[212:213]
	v_lshl_add_u64 v[220:221], v[224:225], 0, v[210:211]
	s_waitcnt lgkmcnt(7)
	v_pk_fma_f32 v[162:163], v[162:163], v[94:95], v[242:243]
	v_pk_fma_f32 v[160:161], v[160:161], v[92:93], v[226:227]
	s_waitcnt lgkmcnt(6)
	v_pk_fma_f32 v[158:159], v[158:159], v[90:91], v[244:245]
	v_pk_fma_f32 v[156:157], v[156:157], v[88:89], v[188:189]
	s_mov_b64 s[74:75], -1
	s_and_b64 vcc, exec, s[8:9]
	v_lshl_add_u64 v[190:191], v[224:225], 1, v[208:209]
	v_lshl_add_u64 v[188:189], v[220:221], 1, s[46:47]
	s_cbranch_vccnz .LBB0_574
	v_mov_b32_e32 v226, v161
	v_mov_b32_e32 v227, v157
	v_mov_b32_e32 v224, v160
	v_mov_b32_e32 v225, v156
	v_pk_mul_f32 v[226:227], v[226:227], v[226:227]
	v_mov_b32_e32 v242, v163
	v_mov_b32_e32 v243, v159
	v_pk_fma_f32 v[224:225], v[224:225], v[224:225], v[226:227]
	v_mov_b32_e32 v226, v162
	v_mov_b32_e32 v227, v158
	v_pk_mul_f32 v[242:243], v[242:243], v[242:243]
	v_cvt_pk_f16_f32 v244, v156, v157
	v_pk_fma_f32 v[226:227], v[226:227], v[226:227], v[242:243]
	v_cvt_pk_f16_f32 v242, v160, v161
	v_pk_add_f32 v[224:225], v[224:225], v[226:227]
	v_cvt_pk_f16_f32 v243, v162, v163
	v_cvt_pk_f16_f32 v245, v158, v159
	v_add_f32_e32 v213, v224, v225
	global_store_dwordx4 v[190:191], v[242:245], off
	s_waitcnt lgkmcnt(5)
	v_pk_mul_f32 v[224:225], v[86:87], v[162:163]
	v_pk_mul_f32 v[226:227], v[84:85], v[160:161]
	s_waitcnt lgkmcnt(4)
	v_pk_mul_f32 v[246:247], v[82:83], v[158:159]
	v_pk_mul_f32 v[244:245], v[80:81], v[156:157]
	v_cvt_pk_bf16_f32 v242, v226, v227
	v_cvt_pk_bf16_f32 v243, v224, v225
	v_cvt_pk_bf16_f32 v244, v244, v245
	v_cvt_pk_bf16_f32 v245, v246, v247
	s_mov_b64 s[74:75], 0
	global_store_dwordx4 v[188:189], v[242:245], off

; __device__ __forceinline__ unsigned cvtpk(float lo, float hi) { f32x2_t v = {lo, hi}; bf16x2_t b = __builtin_convertvector(v, bf16x2_t); return __builtin_bit_cast(unsigned, b); }
; __device__ __forceinline__ unsigned cvtpk_h(float lo, float hi) { f32x2_t v = {lo, hi}; f16x2_t h = __builtin_convertvector(v, f16x2_t); return __builtin_bit_cast(unsigned, h); }
; __device__ __forceinline__ f32x2_t unpk_h(unsigned w) { return __builtin_convertvector(__builtin_bit_cast(f16x2_t, w), f32x2_t); }
;     __device__ __forceinline__ void operator()(const f32x4 (&acc)[2][2][4][2], const Unit& u, int wr, int wc, int fr, int fq, int tid, const Pre& pre) const {
;     ...
;                     const f32x2_t h0 = unpk_h(bw[q][mm][bj].x), h1 = unpk_h(bw[q][mm][bj].y), h2 = unpk_h(bw[q][mm][bj].z), h3 = unpk_h(bw[q][mm][bj].w);
;                     const f32x4 b0 = {h0[0], h0[1], h1[0], h1[1]}, b1 = {h2[0], h2[1], h3[0], h3[1]};
;                     const f32x4 o0 = b0 + gv[bj][0] * acc[ai][bj][m][0], o1 = b1 + gv[bj][1] * acc[ai][bj][m][1];
;                     if (nx) { ss += ((o0[0] * o0[0] + o0[1] * o0[1]) + (o0[2] * o0[2] + o0[3] * o0[3])) + ((o1[0] * o1[0] + o1[1] * o1[1]) + (o1[2] * o1[2] + o1[3] * o1[3]));
;                         u32x4 xw; xw.x = cvtpk_h(o0[0], o0[1]); xw.y = cvtpk_h(o0[2], o0[3]); xw.z = cvtpk_h(o1[0], o1[1]); xw.w = cvtpk_h(o1[2], o1[3]);
;                         __builtin_nontemporal_store(xw, (u32x4*)(xb + off + bj * HALF));
;                         const f32x4 t0 = o0 * gsn[bj][0], t1 = o1 * gsn[bj][1];
;                         u32x4 w; w.x = cvtpk(t0[0], t0[1]); w.y = cvtpk(t0[2], t0[3]); w.z = cvtpk(t1[0], t1[1]); w.w = cvtpk(t1[2], t1[3]);
;                         *(u32x4*)(XT + off + bj * HALF) = w; }
.LBB0_579:
	v_mov_b32_e32 v158, v149
	v_mov_b32_e32 v159, v145
	v_mov_b32_e32 v156, v148
	v_mov_b32_e32 v157, v144
	v_pk_mul_f32 v[158:159], v[158:159], v[158:159]
	v_mov_b32_e32 v160, v151
	v_mov_b32_e32 v161, v147
	v_pk_fma_f32 v[156:157], v[156:157], v[156:157], v[158:159]
	v_mov_b32_e32 v158, v150
	v_mov_b32_e32 v159, v146
	v_pk_mul_f32 v[160:161], v[160:161], v[160:161]
	s_waitcnt lgkmcnt(0)
	v_pk_mul_f32 v[162:163], v[58:59], v[146:147]
	v_pk_fma_f32 v[158:159], v[158:159], v[158:159], v[160:161]
	v_cvt_pk_f16_f32 v160, v144, v145
	v_pk_add_f32 v[156:157], v[156:157], v[158:159]
	v_cvt_pk_f16_f32 v158, v148, v149
	v_cvt_pk_f16_f32 v159, v150, v151
	v_cvt_pk_f16_f32 v161, v146, v147
	v_add_f32_e32 v156, v156, v157
	global_store_dwordx4 v[190:191], v[158:161], off offset:256
	v_pk_mul_f32 v[184:185], v[56:57], v[144:145]
	v_add_f32_e32 v156, v156, v213
	v_pk_mul_f32 v[160:161], v[62:63], v[150:151]
	v_pk_mul_f32 v[158:159], v[60:61], v[148:149]
	s_nop 0
	v_cvt_pk_bf16_f32 v158, v158, v159
	v_cvt_pk_bf16_f32 v159, v160, v161
	v_cvt_pk_bf16_f32 v160, v184, v185
	v_cvt_pk_bf16_f32 v161, v162, v163
	global_store_dwordx4 v[188:189], v[158:161], off offset:256
	s_cbranch_execnz .LBB0_578

; __device__ __forceinline__ unsigned cvtpk(float lo, float hi) { f32x2_t v = {lo, hi}; bf16x2_t b = __builtin_convertvector(v, bf16x2_t); return __builtin_bit_cast(unsigned, b); }
; __device__ __forceinline__ unsigned cvtpk_h(float lo, float hi) { f32x2_t v = {lo, hi}; f16x2_t h = __builtin_convertvector(v, f16x2_t); return __builtin_bit_cast(unsigned, h); }
; __device__ __forceinline__ f32x2_t unpk_h(unsigned w) { return __builtin_convertvector(__builtin_bit_cast(f16x2_t, w), f32x2_t); }
;     __device__ __forceinline__ void operator()(const f32x4 (&acc)[2][2][4][2], const Unit& u, int wr, int wc, int fr, int fq, int tid, const Pre& pre) const {
;     ...
;             for (int mm = 0; mm < 2; ++mm) { const int m = (q & 1) * 2 + mm; const size_t off = (size_t)(row0 + ai * HALF + m * 16) * DM + col0; float ss = 0.f;
; #pragma unroll
;                 for (int bj = 0; bj < 2; ++bj) {
;                     const f32x2_t h0 = unpk_h(bw[q][mm][bj].x), h1 = unpk_h(bw[q][mm][bj].y), h2 = unpk_h(bw[q][mm][bj].z), h3 = unpk_h(bw[q][mm][bj].w);
;                     const f32x4 b0 = {h0[0], h0[1], h1[0], h1[1]}, b1 = {h2[0], h2[1], h3[0], h3[1]};
;                     const f32x4 o0 = b0 + gv[bj][0] * acc[ai][bj][m][0], o1 = b1 + gv[bj][1] * acc[ai][bj][m][1];
;                     if (nx) { ss += ((o0[0] * o0[0] + o0[1] * o0[1]) + (o0[2] * o0[2] + o0[3] * o0[3])) + ((o1[0] * o1[0] + o1[1] * o1[1]) + (o1[2] * o1[2] + o1[3] * o1[3]));
;                         u32x4 xw; xw.x = cvtpk_h(o0[0], o0[1]); xw.y = cvtpk_h(o0[2], o0[3]); xw.z = cvtpk_h(o1[0], o1[1]); xw.w = cvtpk_h(o1[2], o1[3]);
;                         __builtin_nontemporal_store(xw, (u32x4*)(xb + off + bj * HALF));
;                         const f32x4 t0 = o0 * gsn[bj][0], t1 = o1 * gsn[bj][1];
;                         u32x4 w; w.x = cvtpk(t0[0], t0[1]); w.y = cvtpk(t0[2], t0[3]); w.z = cvtpk(t1[0], t1[1]); w.w = cvtpk(t1[2], t1[3]);
;                         *(u32x4*)(XT + off + bj * HALF) = w; }
.LBB0_584:
	v_cvt_f32_f16_sdwa v147, v180 dst_sel:DWORD dst_unused:UNUSED_PAD src0_sel:WORD_1
	v_cvt_f32_f16_e32 v146, v180
	v_cvt_f32_f16_sdwa v151, v181 dst_sel:DWORD dst_unused:UNUSED_PAD src0_sel:WORD_1
	v_cvt_f32_f16_e32 v150, v181
	v_cvt_f32_f16_sdwa v157, v182 dst_sel:DWORD dst_unused:UNUSED_PAD src0_sel:WORD_1
	v_cvt_f32_f16_sdwa v159, v183 dst_sel:DWORD dst_unused:UNUSED_PAD src0_sel:WORD_1
	v_cvt_f32_f16_e32 v158, v183
	v_cvt_f32_f16_e32 v156, v182
	s_waitcnt lgkmcnt(0)
	v_lshlrev_b64 v[144:145], 10, v[218:219]
	v_lshl_add_u64 v[148:149], v[144:145], 0, v[210:211]
	v_pk_fma_f32 v[142:143], v[142:143], v[94:95], v[150:151]
	v_pk_fma_f32 v[140:141], v[140:141], v[92:93], v[146:147]
	v_pk_fma_f32 v[138:139], v[138:139], v[90:91], v[158:159]
	v_pk_fma_f32 v[136:137], v[136:137], v[88:89], v[156:157]
	s_mov_b64 s[74:75], -1
	s_and_b64 vcc, exec, s[8:9]
	v_lshl_add_u64 v[146:147], v[144:145], 1, v[208:209]
	v_lshl_add_u64 v[144:145], v[148:149], 1, s[46:47]
	s_cbranch_vccnz .LBB0_586
	v_mov_b32_e32 v156, v141
	v_mov_b32_e32 v157, v137
	v_mov_b32_e32 v150, v140
	v_mov_b32_e32 v151, v136
	v_pk_mul_f32 v[156:157], v[156:157], v[156:157]
	v_mov_b32_e32 v158, v143
	v_mov_b32_e32 v159, v139
	v_pk_fma_f32 v[150:151], v[150:151], v[150:151], v[156:157]
	v_mov_b32_e32 v156, v142
	v_mov_b32_e32 v157, v138
	v_pk_mul_f32 v[158:159], v[158:159], v[158:159]
	v_pk_mul_f32 v[160:161], v[82:83], v[138:139]
	v_pk_fma_f32 v[156:157], v[156:157], v[156:157], v[158:159]
	v_cvt_pk_f16_f32 v158, v136, v137
	v_pk_add_f32 v[150:151], v[150:151], v[156:157]
	v_cvt_pk_f16_f32 v156, v140, v141
	v_cvt_pk_f16_f32 v157, v142, v143
	v_cvt_pk_f16_f32 v159, v138, v139
	global_store_dwordx4 v[146:147], v[156:159], off
	v_pk_mul_f32 v[162:163], v[80:81], v[136:137]
	v_add_f32_e32 v150, v150, v151
	v_pk_mul_f32 v[158:159], v[86:87], v[142:143]
	v_pk_mul_f32 v[156:157], v[84:85], v[140:141]
	s_mov_b64 s[74:75], 0
	v_cvt_pk_bf16_f32 v156, v156, v157
	v_cvt_pk_bf16_f32 v157, v158, v159
	v_cvt_pk_bf16_f32 v158, v162, v163
	v_cvt_pk_bf16_f32 v159, v160, v161
	global_store_dwordx4 v[144:145], v[156:159], off

; __device__ __forceinline__ unsigned cvtpk(float lo, float hi) { f32x2_t v = {lo, hi}; bf16x2_t b = __builtin_convertvector(v, bf16x2_t); return __builtin_bit_cast(unsigned, b); }
; __device__ __forceinline__ unsigned cvtpk_h(float lo, float hi) { f32x2_t v = {lo, hi}; f16x2_t h = __builtin_convertvector(v, f16x2_t); return __builtin_bit_cast(unsigned, h); }
; __device__ __forceinline__ f32x2_t unpk_h(unsigned w) { return __builtin_convertvector(__builtin_bit_cast(f16x2_t, w), f32x2_t); }
;     __device__ __forceinline__ void operator()(const f32x4 (&acc)[2][2][4][2], const Unit& u, int wr, int wc, int fr, int fq, int tid, const Pre& pre) const {
;     ...
;                     const f32x2_t h0 = unpk_h(bw[q][mm][bj].x), h1 = unpk_h(bw[q][mm][bj].y), h2 = unpk_h(bw[q][mm][bj].z), h3 = unpk_h(bw[q][mm][bj].w);
;                     const f32x4 b0 = {h0[0], h0[1], h1[0], h1[1]}, b1 = {h2[0], h2[1], h3[0], h3[1]};
;                     const f32x4 o0 = b0 + gv[bj][0] * acc[ai][bj][m][0], o1 = b1 + gv[bj][1] * acc[ai][bj][m][1];
;                     if (nx) { ss += ((o0[0] * o0[0] + o0[1] * o0[1]) + (o0[2] * o0[2] + o0[3] * o0[3])) + ((o1[0] * o1[0] + o1[1] * o1[1]) + (o1[2] * o1[2] + o1[3] * o1[3]));
;                         u32x4 xw; xw.x = cvtpk_h(o0[0], o0[1]); xw.y = cvtpk_h(o0[2], o0[3]); xw.z = cvtpk_h(o1[0], o1[1]); xw.w = cvtpk_h(o1[2], o1[3]);
;                         __builtin_nontemporal_store(xw, (u32x4*)(xb + off + bj * HALF));
;                         const f32x4 t0 = o0 * gsn[bj][0], t1 = o1 * gsn[bj][1];
;                         u32x4 w; w.x = cvtpk(t0[0], t0[1]); w.y = cvtpk(t0[2], t0[3]); w.z = cvtpk(t1[0], t1[1]); w.w = cvtpk(t1[2], t1[3]);
;                         *(u32x4*)(XT + off + bj * HALF) = w; }
.LBB0_591:
	v_mov_b32_e32 v138, v133
	v_mov_b32_e32 v139, v129
	v_mov_b32_e32 v136, v132
	v_mov_b32_e32 v137, v128
	v_pk_mul_f32 v[138:139], v[138:139], v[138:139]
	v_mov_b32_e32 v140, v135
	v_mov_b32_e32 v141, v131
	v_pk_fma_f32 v[136:137], v[136:137], v[136:137], v[138:139]
	v_mov_b32_e32 v138, v134
	v_mov_b32_e32 v139, v130
	v_pk_mul_f32 v[140:141], v[140:141], v[140:141]
	v_pk_mul_f32 v[142:143], v[58:59], v[130:131]
	v_pk_fma_f32 v[138:139], v[138:139], v[138:139], v[140:141]
	v_cvt_pk_f16_f32 v140, v128, v129
	v_pk_add_f32 v[136:137], v[136:137], v[138:139]
	v_cvt_pk_f16_f32 v138, v132, v133
	v_cvt_pk_f16_f32 v139, v134, v135
	v_cvt_pk_f16_f32 v141, v130, v131
	v_add_f32_e32 v136, v136, v137
	global_store_dwordx4 v[146:147], v[138:141], off offset:256
	v_pk_mul_f32 v[146:147], v[56:57], v[128:129]
	v_add_f32_e32 v136, v136, v150
	v_pk_mul_f32 v[140:141], v[62:63], v[134:135]
	v_pk_mul_f32 v[138:139], v[60:61], v[132:133]
	s_nop 0
	v_cvt_pk_bf16_f32 v138, v138, v139
	v_cvt_pk_bf16_f32 v139, v140, v141
	v_cvt_pk_bf16_f32 v140, v146, v147
	v_cvt_pk_bf16_f32 v141, v142, v143
	global_store_dwordx4 v[144:145], v[138:141], off offset:256
	s_cbranch_execnz .LBB0_590

; __device__ __forceinline__ unsigned cvtpk(float lo, float hi) { f32x2_t v = {lo, hi}; bf16x2_t b = __builtin_convertvector(v, bf16x2_t); return __builtin_bit_cast(unsigned, b); }
; __device__ __forceinline__ unsigned cvtpk_h(float lo, float hi) { f32x2_t v = {lo, hi}; f16x2_t h = __builtin_convertvector(v, f16x2_t); return __builtin_bit_cast(unsigned, h); }
; __device__ __forceinline__ f32x2_t unpk_h(unsigned w) { return __builtin_convertvector(__builtin_bit_cast(f16x2_t, w), f32x2_t); }
;     __device__ __forceinline__ void operator()(const f32x4 (&acc)[2][2][4][2], const Unit& u, int wr, int wc, int fr, int fq, int tid, const Pre& pre) const {
;     ...
;             for (int mm = 0; mm < 2; ++mm) { const int m = (q & 1) * 2 + mm; const size_t off = (size_t)(row0 + ai * HALF + m * 16) * DM + col0; float ss = 0.f;
; #pragma unroll
;                 for (int bj = 0; bj < 2; ++bj) {
;                     const f32x2_t h0 = unpk_h(bw[q][mm][bj].x), h1 = unpk_h(bw[q][mm][bj].y), h2 = unpk_h(bw[q][mm][bj].z), h3 = unpk_h(bw[q][mm][bj].w);
;                     const f32x4 b0 = {h0[0], h0[1], h1[0], h1[1]}, b1 = {h2[0], h2[1], h3[0], h3[1]};
;                     const f32x4 o0 = b0 + gv[bj][0] * acc[ai][bj][m][0], o1 = b1 + gv[bj][1] * acc[ai][bj][m][1];
;                     if (nx) { ss += ((o0[0] * o0[0] + o0[1] * o0[1]) + (o0[2] * o0[2] + o0[3] * o0[3])) + ((o1[0] * o1[0] + o1[1] * o1[1]) + (o1[2] * o1[2] + o1[3] * o1[3]));
;                         u32x4 xw; xw.x = cvtpk_h(o0[0], o0[1]); xw.y = cvtpk_h(o0[2], o0[3]); xw.z = cvtpk_h(o1[0], o1[1]); xw.w = cvtpk_h(o1[2], o1[3]);
;                         __builtin_nontemporal_store(xw, (u32x4*)(xb + off + bj * HALF));
;                         const f32x4 t0 = o0 * gsn[bj][0], t1 = o1 * gsn[bj][1];
;                         u32x4 w; w.x = cvtpk(t0[0], t0[1]); w.y = cvtpk(t0[2], t0[3]); w.z = cvtpk(t1[0], t1[1]); w.w = cvtpk(t1[2], t1[3]);
;                         *(u32x4*)(XT + off + bj * HALF) = w; }
;     ...
;             if (q == 0) RES_LOAD(2); else if (q == 1) RES_LOAD(3); else asm volatile("" ::: "memory");
.LBB0_596:
	v_add_u32_e32 v146, 0x80, v212
	v_ashrrev_i32_e32 v147, 31, v146
	s_waitcnt lgkmcnt(0)
	v_lshlrev_b64 v[128:129], 11, v[146:147]
	v_add_u32_e32 v144, 0x90, v212
	v_lshl_add_u64 v[128:129], v[208:209], 0, v[128:129]
	v_ashrrev_i32_e32 v145, 31, v144
	global_load_dwordx4 v[140:143], v[128:129], off
	global_load_dwordx4 v[136:139], v[128:129], off offset:256
	v_lshlrev_b64 v[128:129], 11, v[144:145]
	v_lshl_add_u64 v[128:129], v[208:209], 0, v[128:129]
	global_load_dwordx4 v[132:135], v[128:129], off
	s_nop 0
	global_load_dwordx4 v[128:131], v[128:129], off offset:256
	v_cvt_f32_f16_sdwa v151, v172 dst_sel:DWORD dst_unused:UNUSED_PAD src0_sel:WORD_1
	v_cvt_f32_f16_e32 v150, v172
	v_cvt_f32_f16_sdwa v159, v173 dst_sel:DWORD dst_unused:UNUSED_PAD src0_sel:WORD_1
	v_cvt_f32_f16_e32 v158, v173
	v_cvt_f32_f16_sdwa v161, v174 dst_sel:DWORD dst_unused:UNUSED_PAD src0_sel:WORD_1
	v_cvt_f32_f16_sdwa v163, v175 dst_sel:DWORD dst_unused:UNUSED_PAD src0_sel:WORD_1
	v_cvt_f32_f16_e32 v162, v175
	v_cvt_f32_f16_e32 v160, v174
	v_lshlrev_b64 v[148:149], 10, v[216:217]
	v_lshl_add_u64 v[156:157], v[148:149], 0, v[210:211]
	v_pk_fma_f32 v[126:127], v[126:127], v[94:95], v[158:159]
	v_pk_fma_f32 v[124:125], v[124:125], v[92:93], v[150:151]
	v_pk_fma_f32 v[122:123], v[122:123], v[90:91], v[162:163]
	v_pk_fma_f32 v[120:121], v[120:121], v[88:89], v[160:161]
	s_mov_b64 s[74:75], -1
	s_and_b64 vcc, exec, s[8:9]
	v_lshl_add_u64 v[150:151], v[148:149], 1, v[208:209]
	v_lshl_add_u64 v[148:149], v[156:157], 1, s[46:47]
	s_cbranch_vccnz .LBB0_598
	v_mov_b32_e32 v160, v125
	v_mov_b32_e32 v161, v121
	v_mov_b32_e32 v158, v124
	v_mov_b32_e32 v159, v120
	v_pk_mul_f32 v[160:161], v[160:161], v[160:161]
	v_mov_b32_e32 v162, v127
	v_mov_b32_e32 v163, v123
	v_pk_fma_f32 v[158:159], v[158:159], v[158:159], v[160:161]
	v_mov_b32_e32 v160, v126
	v_mov_b32_e32 v161, v122
	v_pk_mul_f32 v[162:163], v[162:163], v[162:163]
	v_pk_mul_f32 v[172:173], v[82:83], v[122:123]
	v_pk_fma_f32 v[160:161], v[160:161], v[160:161], v[162:163]
	v_cvt_pk_f16_f32 v162, v120, v121
	v_pk_add_f32 v[158:159], v[158:159], v[160:161]
	v_cvt_pk_f16_f32 v160, v124, v125
	v_cvt_pk_f16_f32 v161, v126, v127
	v_cvt_pk_f16_f32 v163, v122, v123
	global_store_dwordx4 v[150:151], v[160:163], off
	v_pk_mul_f32 v[174:175], v[80:81], v[120:121]
	v_add_f32_e32 v158, v158, v159
	v_pk_mul_f32 v[162:163], v[86:87], v[126:127]
	v_pk_mul_f32 v[160:161], v[84:85], v[124:125]
	s_mov_b64 s[74:75], 0
	v_cvt_pk_bf16_f32 v160, v160, v161
	v_cvt_pk_bf16_f32 v161, v162, v163
	v_cvt_pk_bf16_f32 v162, v174, v175
	v_cvt_pk_bf16_f32 v163, v172, v173
	global_store_dwordx4 v[148:149], v[160:163], off

; __device__ __forceinline__ unsigned cvtpk(float lo, float hi) { f32x2_t v = {lo, hi}; bf16x2_t b = __builtin_convertvector(v, bf16x2_t); return __builtin_bit_cast(unsigned, b); }
; __device__ __forceinline__ unsigned cvtpk_h(float lo, float hi) { f32x2_t v = {lo, hi}; f16x2_t h = __builtin_convertvector(v, f16x2_t); return __builtin_bit_cast(unsigned, h); }
; __device__ __forceinline__ f32x2_t unpk_h(unsigned w) { return __builtin_convertvector(__builtin_bit_cast(f16x2_t, w), f32x2_t); }
;     __device__ __forceinline__ void operator()(const f32x4 (&acc)[2][2][4][2], const Unit& u, int wr, int wc, int fr, int fq, int tid, const Pre& pre) const {
;     ...
;                     const f32x2_t h0 = unpk_h(bw[q][mm][bj].x), h1 = unpk_h(bw[q][mm][bj].y), h2 = unpk_h(bw[q][mm][bj].z), h3 = unpk_h(bw[q][mm][bj].w);
;                     const f32x4 b0 = {h0[0], h0[1], h1[0], h1[1]}, b1 = {h2[0], h2[1], h3[0], h3[1]};
;                     const f32x4 o0 = b0 + gv[bj][0] * acc[ai][bj][m][0], o1 = b1 + gv[bj][1] * acc[ai][bj][m][1];
;                     if (nx) { ss += ((o0[0] * o0[0] + o0[1] * o0[1]) + (o0[2] * o0[2] + o0[3] * o0[3])) + ((o1[0] * o1[0] + o1[1] * o1[1]) + (o1[2] * o1[2] + o1[3] * o1[3]));
;                         u32x4 xw; xw.x = cvtpk_h(o0[0], o0[1]); xw.y = cvtpk_h(o0[2], o0[3]); xw.z = cvtpk_h(o1[0], o1[1]); xw.w = cvtpk_h(o1[2], o1[3]);
;                         __builtin_nontemporal_store(xw, (u32x4*)(xb + off + bj * HALF));
;                         const f32x4 t0 = o0 * gsn[bj][0], t1 = o1 * gsn[bj][1];
;                         u32x4 w; w.x = cvtpk(t0[0], t0[1]); w.y = cvtpk(t0[2], t0[3]); w.z = cvtpk(t1[0], t1[1]); w.w = cvtpk(t1[2], t1[3]);
;                         *(u32x4*)(XT + off + bj * HALF) = w; }
.LBB0_603:
	v_mov_b32_e32 v122, v117
	v_mov_b32_e32 v123, v113
	v_mov_b32_e32 v120, v116
	v_mov_b32_e32 v121, v112
	v_pk_mul_f32 v[122:123], v[122:123], v[122:123]
	v_mov_b32_e32 v124, v119
	v_mov_b32_e32 v125, v115
	v_pk_fma_f32 v[120:121], v[120:121], v[120:121], v[122:123]
	v_mov_b32_e32 v122, v118
	v_mov_b32_e32 v123, v114
	v_pk_mul_f32 v[124:125], v[124:125], v[124:125]
	v_pk_mul_f32 v[126:127], v[58:59], v[114:115]
	v_pk_fma_f32 v[122:123], v[122:123], v[122:123], v[124:125]
	v_cvt_pk_f16_f32 v124, v112, v113
	v_pk_add_f32 v[120:121], v[120:121], v[122:123]
	v_cvt_pk_f16_f32 v122, v116, v117
	v_cvt_pk_f16_f32 v123, v118, v119
	v_cvt_pk_f16_f32 v125, v114, v115
	v_add_f32_e32 v120, v120, v121
	global_store_dwordx4 v[150:151], v[122:125], off offset:256
	v_pk_mul_f32 v[150:151], v[56:57], v[112:113]
	v_add_f32_e32 v120, v120, v158
	v_pk_mul_f32 v[124:125], v[62:63], v[118:119]
	v_pk_mul_f32 v[122:123], v[60:61], v[116:117]
	s_nop 0
	v_cvt_pk_bf16_f32 v122, v122, v123
	v_cvt_pk_bf16_f32 v123, v124, v125
	v_cvt_pk_bf16_f32 v124, v150, v151
	v_cvt_pk_bf16_f32 v125, v126, v127
	global_store_dwordx4 v[148:149], v[122:125], off offset:256
	s_cbranch_execnz .LBB0_602

; __device__ __forceinline__ unsigned cvtpk(float lo, float hi) { f32x2_t v = {lo, hi}; bf16x2_t b = __builtin_convertvector(v, bf16x2_t); return __builtin_bit_cast(unsigned, b); }
; __device__ __forceinline__ unsigned cvtpk_h(float lo, float hi) { f32x2_t v = {lo, hi}; f16x2_t h = __builtin_convertvector(v, f16x2_t); return __builtin_bit_cast(unsigned, h); }
; __device__ __forceinline__ f32x2_t unpk_h(unsigned w) { return __builtin_convertvector(__builtin_bit_cast(f16x2_t, w), f32x2_t); }
;     __device__ __forceinline__ void operator()(const f32x4 (&acc)[2][2][4][2], const Unit& u, int wr, int wc, int fr, int fq, int tid, const Pre& pre) const {
;     ...
;             for (int mm = 0; mm < 2; ++mm) { const int m = (q & 1) * 2 + mm; const size_t off = (size_t)(row0 + ai * HALF + m * 16) * DM + col0; float ss = 0.f;
; #pragma unroll
;                 for (int bj = 0; bj < 2; ++bj) {
;                     const f32x2_t h0 = unpk_h(bw[q][mm][bj].x), h1 = unpk_h(bw[q][mm][bj].y), h2 = unpk_h(bw[q][mm][bj].z), h3 = unpk_h(bw[q][mm][bj].w);
;                     const f32x4 b0 = {h0[0], h0[1], h1[0], h1[1]}, b1 = {h2[0], h2[1], h3[0], h3[1]};
;                     const f32x4 o0 = b0 + gv[bj][0] * acc[ai][bj][m][0], o1 = b1 + gv[bj][1] * acc[ai][bj][m][1];
;                     if (nx) { ss += ((o0[0] * o0[0] + o0[1] * o0[1]) + (o0[2] * o0[2] + o0[3] * o0[3])) + ((o1[0] * o1[0] + o1[1] * o1[1]) + (o1[2] * o1[2] + o1[3] * o1[3]));
;                         u32x4 xw; xw.x = cvtpk_h(o0[0], o0[1]); xw.y = cvtpk_h(o0[2], o0[3]); xw.z = cvtpk_h(o1[0], o1[1]); xw.w = cvtpk_h(o1[2], o1[3]);
;                         __builtin_nontemporal_store(xw, (u32x4*)(xb + off + bj * HALF));
;                         const f32x4 t0 = o0 * gsn[bj][0], t1 = o1 * gsn[bj][1];
;                         u32x4 w; w.x = cvtpk(t0[0], t0[1]); w.y = cvtpk(t0[2], t0[3]); w.z = cvtpk(t1[0], t1[1]); w.w = cvtpk(t1[2], t1[3]);
;                         *(u32x4*)(XT + off + bj * HALF) = w; }
.LBB0_608:
	v_cvt_f32_f16_sdwa v115, v164 dst_sel:DWORD dst_unused:UNUSED_PAD src0_sel:WORD_1
	v_cvt_f32_f16_e32 v114, v164
	v_cvt_f32_f16_sdwa v119, v165 dst_sel:DWORD dst_unused:UNUSED_PAD src0_sel:WORD_1
	v_cvt_f32_f16_e32 v118, v165
	v_cvt_f32_f16_sdwa v121, v166 dst_sel:DWORD dst_unused:UNUSED_PAD src0_sel:WORD_1
	v_cvt_f32_f16_sdwa v123, v167 dst_sel:DWORD dst_unused:UNUSED_PAD src0_sel:WORD_1
	v_cvt_f32_f16_e32 v122, v167
	v_cvt_f32_f16_e32 v120, v166
	s_waitcnt lgkmcnt(0)
	v_lshlrev_b64 v[112:113], 10, v[214:215]
	v_lshl_add_u64 v[116:117], v[112:113], 0, v[210:211]
	v_pk_fma_f32 v[110:111], v[110:111], v[94:95], v[118:119]
	v_pk_fma_f32 v[108:109], v[108:109], v[92:93], v[114:115]
	v_pk_fma_f32 v[106:107], v[106:107], v[90:91], v[122:123]
	v_pk_fma_f32 v[104:105], v[104:105], v[88:89], v[120:121]
	s_mov_b64 s[74:75], -1
	s_and_b64 vcc, exec, s[8:9]
	v_lshl_add_u64 v[114:115], v[112:113], 1, v[208:209]
	v_lshl_add_u64 v[112:113], v[116:117], 1, s[46:47]
	s_cbranch_vccnz .LBB0_610
	v_mov_b32_e32 v120, v109
	v_mov_b32_e32 v121, v105
	v_mov_b32_e32 v118, v108
	v_mov_b32_e32 v119, v104
	v_pk_mul_f32 v[120:121], v[120:121], v[120:121]
	v_mov_b32_e32 v122, v111
	v_mov_b32_e32 v123, v107
	v_pk_fma_f32 v[118:119], v[118:119], v[118:119], v[120:121]
	v_mov_b32_e32 v120, v110
	v_mov_b32_e32 v121, v106
	v_pk_mul_f32 v[122:123], v[122:123], v[122:123]
	v_pk_mul_f32 v[124:125], v[82:83], v[106:107]
	v_pk_fma_f32 v[120:121], v[120:121], v[120:121], v[122:123]
	v_cvt_pk_f16_f32 v122, v104, v105
	v_pk_add_f32 v[118:119], v[118:119], v[120:121]
	v_cvt_pk_f16_f32 v120, v108, v109
	v_cvt_pk_f16_f32 v121, v110, v111
	v_cvt_pk_f16_f32 v123, v106, v107
	global_store_dwordx4 v[114:115], v[120:123], off
	v_pk_mul_f32 v[126:127], v[80:81], v[104:105]
	v_add_f32_e32 v118, v118, v119
	v_pk_mul_f32 v[122:123], v[86:87], v[110:111]
	v_pk_mul_f32 v[120:121], v[84:85], v[108:109]
	s_mov_b64 s[74:75], 0
	v_cvt_pk_bf16_f32 v120, v120, v121
	v_cvt_pk_bf16_f32 v121, v122, v123
	v_cvt_pk_bf16_f32 v122, v126, v127
	v_cvt_pk_bf16_f32 v123, v124, v125
	global_store_dwordx4 v[112:113], v[120:123], off

; __device__ __forceinline__ unsigned cvtpk(float lo, float hi) { f32x2_t v = {lo, hi}; bf16x2_t b = __builtin_convertvector(v, bf16x2_t); return __builtin_bit_cast(unsigned, b); }
; __device__ __forceinline__ unsigned cvtpk_h(float lo, float hi) { f32x2_t v = {lo, hi}; f16x2_t h = __builtin_convertvector(v, f16x2_t); return __builtin_bit_cast(unsigned, h); }
; __device__ __forceinline__ f32x2_t unpk_h(unsigned w) { return __builtin_convertvector(__builtin_bit_cast(f16x2_t, w), f32x2_t); }
;     __device__ __forceinline__ void operator()(const f32x4 (&acc)[2][2][4][2], const Unit& u, int wr, int wc, int fr, int fq, int tid, const Pre& pre) const {
;     ...
;                     const f32x2_t h0 = unpk_h(bw[q][mm][bj].x), h1 = unpk_h(bw[q][mm][bj].y), h2 = unpk_h(bw[q][mm][bj].z), h3 = unpk_h(bw[q][mm][bj].w);
;                     const f32x4 b0 = {h0[0], h0[1], h1[0], h1[1]}, b1 = {h2[0], h2[1], h3[0], h3[1]};
;                     const f32x4 o0 = b0 + gv[bj][0] * acc[ai][bj][m][0], o1 = b1 + gv[bj][1] * acc[ai][bj][m][1];
;                     if (nx) { ss += ((o0[0] * o0[0] + o0[1] * o0[1]) + (o0[2] * o0[2] + o0[3] * o0[3])) + ((o1[0] * o1[0] + o1[1] * o1[1]) + (o1[2] * o1[2] + o1[3] * o1[3]));
;                         u32x4 xw; xw.x = cvtpk_h(o0[0], o0[1]); xw.y = cvtpk_h(o0[2], o0[3]); xw.z = cvtpk_h(o1[0], o1[1]); xw.w = cvtpk_h(o1[2], o1[3]);
;                         __builtin_nontemporal_store(xw, (u32x4*)(xb + off + bj * HALF));
;                         const f32x4 t0 = o0 * gsn[bj][0], t1 = o1 * gsn[bj][1];
;                         u32x4 w; w.x = cvtpk(t0[0], t0[1]); w.y = cvtpk(t0[2], t0[3]); w.z = cvtpk(t1[0], t1[1]); w.w = cvtpk(t1[2], t1[3]);
;                         *(u32x4*)(XT + off + bj * HALF) = w; }
.LBB0_615:
	v_mov_b32_e32 v106, v101
	v_mov_b32_e32 v107, v97
	v_mov_b32_e32 v104, v100
	v_mov_b32_e32 v105, v96
	v_pk_mul_f32 v[106:107], v[106:107], v[106:107]
	v_mov_b32_e32 v108, v103
	v_mov_b32_e32 v109, v99
	v_pk_fma_f32 v[104:105], v[104:105], v[104:105], v[106:107]
	v_mov_b32_e32 v106, v102
	v_mov_b32_e32 v107, v98
	v_pk_mul_f32 v[108:109], v[108:109], v[108:109]
	v_pk_mul_f32 v[110:111], v[58:59], v[98:99]
	v_pk_fma_f32 v[106:107], v[106:107], v[106:107], v[108:109]
	v_cvt_pk_f16_f32 v108, v96, v97
	v_pk_add_f32 v[104:105], v[104:105], v[106:107]
	v_cvt_pk_f16_f32 v106, v100, v101
	v_cvt_pk_f16_f32 v107, v102, v103
	v_cvt_pk_f16_f32 v109, v98, v99
	v_add_f32_e32 v104, v104, v105
	global_store_dwordx4 v[114:115], v[106:109], off offset:256
	v_pk_mul_f32 v[114:115], v[56:57], v[96:97]
	v_add_f32_e32 v104, v104, v118
	v_pk_mul_f32 v[108:109], v[62:63], v[102:103]
	v_pk_mul_f32 v[106:107], v[60:61], v[100:101]
	s_nop 0
	v_cvt_pk_bf16_f32 v106, v106, v107
	v_cvt_pk_bf16_f32 v107, v108, v109
	v_cvt_pk_bf16_f32 v108, v114, v115
	v_cvt_pk_bf16_f32 v109, v110, v111
	global_store_dwordx4 v[112:113], v[106:109], off offset:256
	s_cbranch_execnz .LBB0_614

; __device__ __forceinline__ unsigned cvtpk(float lo, float hi) { f32x2_t v = {lo, hi}; bf16x2_t b = __builtin_convertvector(v, bf16x2_t); return __builtin_bit_cast(unsigned, b); }
; __device__ __forceinline__ unsigned cvtpk_h(float lo, float hi) { f32x2_t v = {lo, hi}; f16x2_t h = __builtin_convertvector(v, f16x2_t); return __builtin_bit_cast(unsigned, h); }
; __device__ __forceinline__ f32x2_t unpk_h(unsigned w) { return __builtin_convertvector(__builtin_bit_cast(f16x2_t, w), f32x2_t); }
;     __device__ __forceinline__ void operator()(const f32x4 (&acc)[2][2][4][2], const Unit& u, int wr, int wc, int fr, int fq, int tid, const Pre& pre) const {
;     ...
;             for (int mm = 0; mm < 2; ++mm) { const int m = (q & 1) * 2 + mm; const size_t off = (size_t)(row0 + ai * HALF + m * 16) * DM + col0; float ss = 0.f;
; #pragma unroll
;                 for (int bj = 0; bj < 2; ++bj) {
;                     const f32x2_t h0 = unpk_h(bw[q][mm][bj].x), h1 = unpk_h(bw[q][mm][bj].y), h2 = unpk_h(bw[q][mm][bj].z), h3 = unpk_h(bw[q][mm][bj].w);
;                     const f32x4 b0 = {h0[0], h0[1], h1[0], h1[1]}, b1 = {h2[0], h2[1], h3[0], h3[1]};
;                     const f32x4 o0 = b0 + gv[bj][0] * acc[ai][bj][m][0], o1 = b1 + gv[bj][1] * acc[ai][bj][m][1];
;                     if (nx) { ss += ((o0[0] * o0[0] + o0[1] * o0[1]) + (o0[2] * o0[2] + o0[3] * o0[3])) + ((o1[0] * o1[0] + o1[1] * o1[1]) + (o1[2] * o1[2] + o1[3] * o1[3]));
;                         u32x4 xw; xw.x = cvtpk_h(o0[0], o0[1]); xw.y = cvtpk_h(o0[2], o0[3]); xw.z = cvtpk_h(o1[0], o1[1]); xw.w = cvtpk_h(o1[2], o1[3]);
;                         __builtin_nontemporal_store(xw, (u32x4*)(xb + off + bj * HALF));
;                         const f32x4 t0 = o0 * gsn[bj][0], t1 = o1 * gsn[bj][1];
;                         u32x4 w; w.x = cvtpk(t0[0], t0[1]); w.y = cvtpk(t0[2], t0[3]); w.z = cvtpk(t1[0], t1[1]); w.w = cvtpk(t1[2], t1[3]);
;                         *(u32x4*)(XT + off + bj * HALF) = w; }
;     ...
;             if (q == 0) RES_LOAD(2); else if (q == 1) RES_LOAD(3); else asm volatile("" ::: "memory");
.LBB0_620:
	v_add_u32_e32 v114, 0xa0, v212
	v_ashrrev_i32_e32 v115, 31, v114
	s_waitcnt lgkmcnt(0)
	v_lshlrev_b64 v[96:97], 11, v[114:115]
	v_add_u32_e32 v112, 0xb0, v212
	v_lshl_add_u64 v[96:97], v[208:209], 0, v[96:97]
	v_ashrrev_i32_e32 v113, 31, v112
	global_load_dwordx4 v[108:111], v[96:97], off
	global_load_dwordx4 v[104:107], v[96:97], off offset:256
	v_lshlrev_b64 v[96:97], 11, v[112:113]
	v_lshl_add_u64 v[96:97], v[208:209], 0, v[96:97]
	global_load_dwordx4 v[100:103], v[96:97], off
	s_nop 0
	global_load_dwordx4 v[96:99], v[96:97], off offset:256
	s_waitcnt vmcnt(7)
	v_cvt_f32_f16_sdwa v119, v140 dst_sel:DWORD dst_unused:UNUSED_PAD src0_sel:WORD_1
	v_cvt_f32_f16_e32 v118, v140
	v_cvt_f32_f16_sdwa v123, v141 dst_sel:DWORD dst_unused:UNUSED_PAD src0_sel:WORD_1
	v_cvt_f32_f16_e32 v122, v141
	v_cvt_f32_f16_sdwa v125, v142 dst_sel:DWORD dst_unused:UNUSED_PAD src0_sel:WORD_1
	v_cvt_f32_f16_sdwa v127, v143 dst_sel:DWORD dst_unused:UNUSED_PAD src0_sel:WORD_1
	v_cvt_f32_f16_e32 v126, v143
	v_cvt_f32_f16_e32 v124, v142
	v_lshlrev_b64 v[116:117], 10, v[146:147]
	v_lshl_add_u64 v[120:121], v[116:117], 0, v[210:211]
	v_pk_fma_f32 v[78:79], v[78:79], v[94:95], v[122:123]
	v_pk_fma_f32 v[76:77], v[76:77], v[92:93], v[118:119]
	v_pk_fma_f32 v[74:75], v[74:75], v[90:91], v[126:127]
	v_pk_fma_f32 v[72:73], v[72:73], v[88:89], v[124:125]
	s_mov_b64 s[74:75], -1
	s_and_b64 vcc, exec, s[8:9]
	v_lshl_add_u64 v[118:119], v[116:117], 1, v[208:209]
	v_lshl_add_u64 v[116:117], v[120:121], 1, s[46:47]
	s_cbranch_vccnz .LBB0_622
	v_mov_b32_e32 v124, v77
	v_mov_b32_e32 v125, v73
	v_mov_b32_e32 v122, v76
	v_mov_b32_e32 v123, v72
	v_pk_mul_f32 v[124:125], v[124:125], v[124:125]
	v_mov_b32_e32 v126, v79
	v_mov_b32_e32 v127, v75
	v_pk_fma_f32 v[122:123], v[122:123], v[122:123], v[124:125]
	v_mov_b32_e32 v124, v78
	v_mov_b32_e32 v125, v74
	v_pk_mul_f32 v[126:127], v[126:127], v[126:127]
	v_pk_mul_f32 v[140:141], v[82:83], v[74:75]
	v_pk_fma_f32 v[124:125], v[124:125], v[124:125], v[126:127]
	v_cvt_pk_f16_f32 v126, v72, v73
	v_pk_add_f32 v[122:123], v[122:123], v[124:125]
	v_cvt_pk_f16_f32 v124, v76, v77
	v_cvt_pk_f16_f32 v125, v78, v79
	v_cvt_pk_f16_f32 v127, v74, v75
	global_store_dwordx4 v[118:119], v[124:127], off
	v_pk_mul_f32 v[142:143], v[80:81], v[72:73]
	v_add_f32_e32 v122, v122, v123
	v_pk_mul_f32 v[126:127], v[86:87], v[78:79]
	v_pk_mul_f32 v[124:125], v[84:85], v[76:77]
	s_mov_b64 s[74:75], 0
	v_cvt_pk_bf16_f32 v124, v124, v125
	v_cvt_pk_bf16_f32 v125, v126, v127
	v_cvt_pk_bf16_f32 v126, v142, v143
	v_cvt_pk_bf16_f32 v127, v140, v141
	global_store_dwordx4 v[116:117], v[124:127], off

; __device__ __forceinline__ unsigned cvtpk(float lo, float hi) { f32x2_t v = {lo, hi}; bf16x2_t b = __builtin_convertvector(v, bf16x2_t); return __builtin_bit_cast(unsigned, b); }
; __device__ __forceinline__ unsigned cvtpk_h(float lo, float hi) { f32x2_t v = {lo, hi}; f16x2_t h = __builtin_convertvector(v, f16x2_t); return __builtin_bit_cast(unsigned, h); }
; __device__ __forceinline__ f32x2_t unpk_h(unsigned w) { return __builtin_convertvector(__builtin_bit_cast(f16x2_t, w), f32x2_t); }
;     __device__ __forceinline__ void operator()(const f32x4 (&acc)[2][2][4][2], const Unit& u, int wr, int wc, int fr, int fq, int tid, const Pre& pre) const {
;     ...
;                     const f32x2_t h0 = unpk_h(bw[q][mm][bj].x), h1 = unpk_h(bw[q][mm][bj].y), h2 = unpk_h(bw[q][mm][bj].z), h3 = unpk_h(bw[q][mm][bj].w);
;                     const f32x4 b0 = {h0[0], h0[1], h1[0], h1[1]}, b1 = {h2[0], h2[1], h3[0], h3[1]};
;                     const f32x4 o0 = b0 + gv[bj][0] * acc[ai][bj][m][0], o1 = b1 + gv[bj][1] * acc[ai][bj][m][1];
;                     if (nx) { ss += ((o0[0] * o0[0] + o0[1] * o0[1]) + (o0[2] * o0[2] + o0[3] * o0[3])) + ((o1[0] * o1[0] + o1[1] * o1[1]) + (o1[2] * o1[2] + o1[3] * o1[3]));
;                         u32x4 xw; xw.x = cvtpk_h(o0[0], o0[1]); xw.y = cvtpk_h(o0[2], o0[3]); xw.z = cvtpk_h(o1[0], o1[1]); xw.w = cvtpk_h(o1[2], o1[3]);
;                         __builtin_nontemporal_store(xw, (u32x4*)(xb + off + bj * HALF));
;                         const f32x4 t0 = o0 * gsn[bj][0], t1 = o1 * gsn[bj][1];
;                         u32x4 w; w.x = cvtpk(t0[0], t0[1]); w.y = cvtpk(t0[2], t0[3]); w.z = cvtpk(t1[0], t1[1]); w.w = cvtpk(t1[2], t1[3]);
;                         *(u32x4*)(XT + off + bj * HALF) = w; }
.LBB0_627:
	v_mov_b32_e32 v74, v53
	v_mov_b32_e32 v75, v49
	v_mov_b32_e32 v72, v52
	v_mov_b32_e32 v73, v48
	v_pk_mul_f32 v[74:75], v[74:75], v[74:75]
	v_mov_b32_e32 v76, v55
	v_mov_b32_e32 v77, v51
	v_pk_fma_f32 v[72:73], v[72:73], v[72:73], v[74:75]
	v_mov_b32_e32 v74, v54
	v_mov_b32_e32 v75, v50
	v_pk_mul_f32 v[76:77], v[76:77], v[76:77]
	v_pk_mul_f32 v[78:79], v[58:59], v[50:51]
	v_pk_fma_f32 v[74:75], v[74:75], v[74:75], v[76:77]
	v_cvt_pk_f16_f32 v76, v48, v49
	v_pk_add_f32 v[72:73], v[72:73], v[74:75]
	v_cvt_pk_f16_f32 v74, v52, v53
	v_cvt_pk_f16_f32 v75, v54, v55
	v_cvt_pk_f16_f32 v77, v50, v51
	v_add_f32_e32 v72, v72, v73
	global_store_dwordx4 v[118:119], v[74:77], off offset:256
	v_pk_mul_f32 v[118:119], v[56:57], v[48:49]
	v_add_f32_e32 v72, v72, v122
	v_pk_mul_f32 v[76:77], v[62:63], v[54:55]
	v_pk_mul_f32 v[74:75], v[60:61], v[52:53]
	s_nop 0
	v_cvt_pk_bf16_f32 v74, v74, v75
	v_cvt_pk_bf16_f32 v75, v76, v77
	v_cvt_pk_bf16_f32 v76, v118, v119
	v_cvt_pk_bf16_f32 v77, v78, v79
	global_store_dwordx4 v[116:117], v[74:77], off offset:256
	s_cbranch_execnz .LBB0_626

; __device__ __forceinline__ unsigned cvtpk(float lo, float hi) { f32x2_t v = {lo, hi}; bf16x2_t b = __builtin_convertvector(v, bf16x2_t); return __builtin_bit_cast(unsigned, b); }
; __device__ __forceinline__ unsigned cvtpk_h(float lo, float hi) { f32x2_t v = {lo, hi}; f16x2_t h = __builtin_convertvector(v, f16x2_t); return __builtin_bit_cast(unsigned, h); }
; __device__ __forceinline__ f32x2_t unpk_h(unsigned w) { return __builtin_convertvector(__builtin_bit_cast(f16x2_t, w), f32x2_t); }
;     __device__ __forceinline__ void operator()(const f32x4 (&acc)[2][2][4][2], const Unit& u, int wr, int wc, int fr, int fq, int tid, const Pre& pre) const {
;     ...
;             for (int mm = 0; mm < 2; ++mm) { const int m = (q & 1) * 2 + mm; const size_t off = (size_t)(row0 + ai * HALF + m * 16) * DM + col0; float ss = 0.f;
; #pragma unroll
;                 for (int bj = 0; bj < 2; ++bj) {
;                     const f32x2_t h0 = unpk_h(bw[q][mm][bj].x), h1 = unpk_h(bw[q][mm][bj].y), h2 = unpk_h(bw[q][mm][bj].z), h3 = unpk_h(bw[q][mm][bj].w);
;                     const f32x4 b0 = {h0[0], h0[1], h1[0], h1[1]}, b1 = {h2[0], h2[1], h3[0], h3[1]};
;                     const f32x4 o0 = b0 + gv[bj][0] * acc[ai][bj][m][0], o1 = b1 + gv[bj][1] * acc[ai][bj][m][1];
;                     if (nx) { ss += ((o0[0] * o0[0] + o0[1] * o0[1]) + (o0[2] * o0[2] + o0[3] * o0[3])) + ((o1[0] * o1[0] + o1[1] * o1[1]) + (o1[2] * o1[2] + o1[3] * o1[3]));
;                         u32x4 xw; xw.x = cvtpk_h(o0[0], o0[1]); xw.y = cvtpk_h(o0[2], o0[3]); xw.z = cvtpk_h(o1[0], o1[1]); xw.w = cvtpk_h(o1[2], o1[3]);
;                         __builtin_nontemporal_store(xw, (u32x4*)(xb + off + bj * HALF));
;                         const f32x4 t0 = o0 * gsn[bj][0], t1 = o1 * gsn[bj][1];
;                         u32x4 w; w.x = cvtpk(t0[0], t0[1]); w.y = cvtpk(t0[2], t0[3]); w.z = cvtpk(t1[0], t1[1]); w.w = cvtpk(t1[2], t1[3]);
;                         *(u32x4*)(XT + off + bj * HALF) = w; }
.LBB0_632:
	s_waitcnt vmcnt(5)
	v_cvt_f32_f16_sdwa v51, v132 dst_sel:DWORD dst_unused:UNUSED_PAD src0_sel:WORD_1
	v_cvt_f32_f16_e32 v50, v132
	v_cvt_f32_f16_sdwa v55, v133 dst_sel:DWORD dst_unused:UNUSED_PAD src0_sel:WORD_1
	v_cvt_f32_f16_e32 v54, v133
	v_cvt_f32_f16_sdwa v73, v134 dst_sel:DWORD dst_unused:UNUSED_PAD src0_sel:WORD_1
	v_cvt_f32_f16_sdwa v75, v135 dst_sel:DWORD dst_unused:UNUSED_PAD src0_sel:WORD_1
	v_cvt_f32_f16_e32 v74, v135
	v_cvt_f32_f16_e32 v72, v134
	s_waitcnt lgkmcnt(0)
	v_lshlrev_b64 v[48:49], 10, v[144:145]
	v_lshl_add_u64 v[52:53], v[48:49], 0, v[210:211]
	v_pk_fma_f32 v[46:47], v[46:47], v[94:95], v[54:55]
	v_pk_fma_f32 v[44:45], v[44:45], v[92:93], v[50:51]
	v_pk_fma_f32 v[42:43], v[42:43], v[90:91], v[74:75]
	v_pk_fma_f32 v[40:41], v[40:41], v[88:89], v[72:73]
	s_mov_b64 s[74:75], -1
	s_and_b64 vcc, exec, s[8:9]
	v_lshl_add_u64 v[50:51], v[48:49], 1, v[208:209]
	v_lshl_add_u64 v[48:49], v[52:53], 1, s[46:47]
	s_cbranch_vccnz .LBB0_634
	v_mov_b32_e32 v72, v45
	v_mov_b32_e32 v73, v41
	v_mov_b32_e32 v54, v44
	v_mov_b32_e32 v55, v40
	v_pk_mul_f32 v[72:73], v[72:73], v[72:73]
	v_mov_b32_e32 v74, v47
	v_mov_b32_e32 v75, v43
	v_pk_fma_f32 v[54:55], v[54:55], v[54:55], v[72:73]
	v_mov_b32_e32 v72, v46
	v_mov_b32_e32 v73, v42
	v_pk_mul_f32 v[74:75], v[74:75], v[74:75]
	v_pk_mul_f32 v[76:77], v[82:83], v[42:43]
	v_pk_fma_f32 v[72:73], v[72:73], v[72:73], v[74:75]
	v_cvt_pk_f16_f32 v74, v40, v41
	v_pk_add_f32 v[54:55], v[54:55], v[72:73]
	v_cvt_pk_f16_f32 v72, v44, v45
	v_cvt_pk_f16_f32 v73, v46, v47
	v_cvt_pk_f16_f32 v75, v42, v43
	global_store_dwordx4 v[50:51], v[72:75], off
	v_pk_mul_f32 v[78:79], v[80:81], v[40:41]
	v_add_f32_e32 v54, v54, v55
	v_pk_mul_f32 v[74:75], v[86:87], v[46:47]
	v_pk_mul_f32 v[72:73], v[84:85], v[44:45]
	s_mov_b64 s[74:75], 0
	v_cvt_pk_bf16_f32 v72, v72, v73
	v_cvt_pk_bf16_f32 v73, v74, v75
	v_cvt_pk_bf16_f32 v74, v78, v79
	v_cvt_pk_bf16_f32 v75, v76, v77
	global_store_dwordx4 v[48:49], v[72:75], off

; __device__ __forceinline__ unsigned cvtpk(float lo, float hi) { f32x2_t v = {lo, hi}; bf16x2_t b = __builtin_convertvector(v, bf16x2_t); return __builtin_bit_cast(unsigned, b); }
; __device__ __forceinline__ unsigned cvtpk_h(float lo, float hi) { f32x2_t v = {lo, hi}; f16x2_t h = __builtin_convertvector(v, f16x2_t); return __builtin_bit_cast(unsigned, h); }
; __device__ __forceinline__ f32x2_t unpk_h(unsigned w) { return __builtin_convertvector(__builtin_bit_cast(f16x2_t, w), f32x2_t); }
;     __device__ __forceinline__ void operator()(const f32x4 (&acc)[2][2][4][2], const Unit& u, int wr, int wc, int fr, int fq, int tid, const Pre& pre) const {
;     ...
;                 for (int bj = 0; bj < 2; ++bj) {
;                     const f32x2_t h0 = unpk_h(bw[q][mm][bj].x), h1 = unpk_h(bw[q][mm][bj].y), h2 = unpk_h(bw[q][mm][bj].z), h3 = unpk_h(bw[q][mm][bj].w);
;                     const f32x4 b0 = {h0[0], h0[1], h1[0], h1[1]}, b1 = {h2[0], h2[1], h3[0], h3[1]};
;                     const f32x4 o0 = b0 + gv[bj][0] * acc[ai][bj][m][0], o1 = b1 + gv[bj][1] * acc[ai][bj][m][1];
;                     if (nx) { ss += ((o0[0] * o0[0] + o0[1] * o0[1]) + (o0[2] * o0[2] + o0[3] * o0[3])) + ((o1[0] * o1[0] + o1[1] * o1[1]) + (o1[2] * o1[2] + o1[3] * o1[3]));
;                         u32x4 xw; xw.x = cvtpk_h(o0[0], o0[1]); xw.y = cvtpk_h(o0[2], o0[3]); xw.z = cvtpk_h(o1[0], o1[1]); xw.w = cvtpk_h(o1[2], o1[3]);
;                         __builtin_nontemporal_store(xw, (u32x4*)(xb + off + bj * HALF));
;                         const f32x4 t0 = o0 * gsn[bj][0], t1 = o1 * gsn[bj][1];
;                         u32x4 w; w.x = cvtpk(t0[0], t0[1]); w.y = cvtpk(t0[2], t0[3]); w.z = cvtpk(t1[0], t1[1]); w.w = cvtpk(t1[2], t1[3]);
;                         *(u32x4*)(XT + off + bj * HALF) = w; }
.LBB0_639:
	v_mov_b32_e32 v42, v37
	v_mov_b32_e32 v43, v33
	v_mov_b32_e32 v40, v36
	v_mov_b32_e32 v41, v32
	v_pk_mul_f32 v[42:43], v[42:43], v[42:43]
	v_mov_b32_e32 v44, v39
	v_mov_b32_e32 v45, v35
	v_pk_fma_f32 v[40:41], v[40:41], v[40:41], v[42:43]
	v_mov_b32_e32 v42, v38
	v_mov_b32_e32 v43, v34
	v_pk_mul_f32 v[44:45], v[44:45], v[44:45]
	v_pk_mul_f32 v[46:47], v[58:59], v[34:35]
	v_pk_fma_f32 v[42:43], v[42:43], v[42:43], v[44:45]
	v_cvt_pk_f16_f32 v44, v32, v33
	v_pk_add_f32 v[40:41], v[40:41], v[42:43]
	v_cvt_pk_f16_f32 v42, v36, v37
	v_cvt_pk_f16_f32 v43, v38, v39
	v_cvt_pk_f16_f32 v45, v34, v35
	v_add_f32_e32 v40, v40, v41
	global_store_dwordx4 v[50:51], v[42:45], off offset:256
	v_pk_mul_f32 v[50:51], v[56:57], v[32:33]
	v_add_f32_e32 v40, v40, v54
	v_pk_mul_f32 v[44:45], v[62:63], v[38:39]
	v_pk_mul_f32 v[42:43], v[60:61], v[36:37]
	s_nop 0
	v_cvt_pk_bf16_f32 v42, v42, v43
	v_cvt_pk_bf16_f32 v43, v44, v45
	v_cvt_pk_bf16_f32 v44, v50, v51
	v_cvt_pk_bf16_f32 v45, v46, v47
	global_store_dwordx4 v[48:49], v[42:45], off offset:256
	s_cbranch_execnz .LBB0_638

; __device__ __forceinline__ unsigned cvtpk(float lo, float hi) { f32x2_t v = {lo, hi}; bf16x2_t b = __builtin_convertvector(v, bf16x2_t); return __builtin_bit_cast(unsigned, b); }
; __device__ __forceinline__ unsigned cvtpk_h(float lo, float hi) { f32x2_t v = {lo, hi}; f16x2_t h = __builtin_convertvector(v, f16x2_t); return __builtin_bit_cast(unsigned, h); }
; __device__ __forceinline__ f32x2_t unpk_h(unsigned w) { return __builtin_convertvector(__builtin_bit_cast(f16x2_t, w), f32x2_t); }
;     __device__ __forceinline__ void operator()(const f32x4 (&acc)[2][2][4][2], const Unit& u, int wr, int wc, int fr, int fq, int tid, const Pre& pre) const {
;     ...
;             for (int mm = 0; mm < 2; ++mm) { const int m = (q & 1) * 2 + mm; const size_t off = (size_t)(row0 + ai * HALF + m * 16) * DM + col0; float ss = 0.f;
; #pragma unroll
;                 for (int bj = 0; bj < 2; ++bj) {
;                     const f32x2_t h0 = unpk_h(bw[q][mm][bj].x), h1 = unpk_h(bw[q][mm][bj].y), h2 = unpk_h(bw[q][mm][bj].z), h3 = unpk_h(bw[q][mm][bj].w);
;                     const f32x4 b0 = {h0[0], h0[1], h1[0], h1[1]}, b1 = {h2[0], h2[1], h3[0], h3[1]};
;                     const f32x4 o0 = b0 + gv[bj][0] * acc[ai][bj][m][0], o1 = b1 + gv[bj][1] * acc[ai][bj][m][1];
;                     if (nx) { ss += ((o0[0] * o0[0] + o0[1] * o0[1]) + (o0[2] * o0[2] + o0[3] * o0[3])) + ((o1[0] * o1[0] + o1[1] * o1[1]) + (o1[2] * o1[2] + o1[3] * o1[3]));
;                         u32x4 xw; xw.x = cvtpk_h(o0[0], o0[1]); xw.y = cvtpk_h(o0[2], o0[3]); xw.z = cvtpk_h(o1[0], o1[1]); xw.w = cvtpk_h(o1[2], o1[3]);
;                         __builtin_nontemporal_store(xw, (u32x4*)(xb + off + bj * HALF));
;                         const f32x4 t0 = o0 * gsn[bj][0], t1 = o1 * gsn[bj][1];
;                         u32x4 w; w.x = cvtpk(t0[0], t0[1]); w.y = cvtpk(t0[2], t0[3]); w.z = cvtpk(t1[0], t1[1]); w.w = cvtpk(t1[2], t1[3]);
;                         *(u32x4*)(XT + off + bj * HALF) = w; }
.LBB0_644:
	s_waitcnt vmcnt(3)
	v_cvt_f32_f16_sdwa v35, v108 dst_sel:DWORD dst_unused:UNUSED_PAD src0_sel:WORD_1
	v_cvt_f32_f16_e32 v34, v108
	v_cvt_f32_f16_sdwa v39, v109 dst_sel:DWORD dst_unused:UNUSED_PAD src0_sel:WORD_1
	v_cvt_f32_f16_e32 v38, v109
	v_cvt_f32_f16_sdwa v41, v110 dst_sel:DWORD dst_unused:UNUSED_PAD src0_sel:WORD_1
	v_cvt_f32_f16_sdwa v43, v111 dst_sel:DWORD dst_unused:UNUSED_PAD src0_sel:WORD_1
	v_cvt_f32_f16_e32 v42, v111
	v_cvt_f32_f16_e32 v40, v110
	s_waitcnt lgkmcnt(0)
	v_lshlrev_b64 v[32:33], 10, v[114:115]
	v_lshl_add_u64 v[36:37], v[32:33], 0, v[210:211]
	v_pk_fma_f32 v[30:31], v[30:31], v[94:95], v[38:39]
	v_pk_fma_f32 v[28:29], v[28:29], v[92:93], v[34:35]
	v_pk_fma_f32 v[26:27], v[26:27], v[90:91], v[42:43]
	v_pk_fma_f32 v[24:25], v[24:25], v[88:89], v[40:41]
	s_mov_b64 s[74:75], -1
	s_and_b64 vcc, exec, s[8:9]
	v_lshl_add_u64 v[34:35], v[32:33], 1, v[208:209]
	v_lshl_add_u64 v[32:33], v[36:37], 1, s[46:47]
	s_cbranch_vccnz .LBB0_646
	v_mov_b32_e32 v40, v29
	v_mov_b32_e32 v41, v25
	v_mov_b32_e32 v38, v28
	v_mov_b32_e32 v39, v24
	v_pk_mul_f32 v[40:41], v[40:41], v[40:41]
	v_mov_b32_e32 v42, v31
	v_mov_b32_e32 v43, v27
	v_pk_fma_f32 v[38:39], v[38:39], v[38:39], v[40:41]
	v_mov_b32_e32 v40, v30
	v_mov_b32_e32 v41, v26
	v_pk_mul_f32 v[42:43], v[42:43], v[42:43]
	v_pk_mul_f32 v[44:45], v[82:83], v[26:27]
	v_pk_fma_f32 v[40:41], v[40:41], v[40:41], v[42:43]
	v_cvt_pk_f16_f32 v42, v24, v25
	v_pk_add_f32 v[38:39], v[38:39], v[40:41]
	v_cvt_pk_f16_f32 v40, v28, v29
	v_cvt_pk_f16_f32 v41, v30, v31
	v_cvt_pk_f16_f32 v43, v26, v27
	global_store_dwordx4 v[34:35], v[40:43], off
	v_pk_mul_f32 v[46:47], v[80:81], v[24:25]
	v_add_f32_e32 v38, v38, v39
	v_pk_mul_f32 v[42:43], v[86:87], v[30:31]
	v_pk_mul_f32 v[40:41], v[84:85], v[28:29]
	s_mov_b64 s[74:75], 0
	v_cvt_pk_bf16_f32 v40, v40, v41
	v_cvt_pk_bf16_f32 v41, v42, v43
	v_cvt_pk_bf16_f32 v42, v46, v47
	v_cvt_pk_bf16_f32 v43, v44, v45
	global_store_dwordx4 v[32:33], v[40:43], off

; __device__ __forceinline__ unsigned cvtpk(float lo, float hi) { f32x2_t v = {lo, hi}; bf16x2_t b = __builtin_convertvector(v, bf16x2_t); return __builtin_bit_cast(unsigned, b); }
; __device__ __forceinline__ unsigned cvtpk_h(float lo, float hi) { f32x2_t v = {lo, hi}; f16x2_t h = __builtin_convertvector(v, f16x2_t); return __builtin_bit_cast(unsigned, h); }
; __device__ __forceinline__ f32x2_t unpk_h(unsigned w) { return __builtin_convertvector(__builtin_bit_cast(f16x2_t, w), f32x2_t); }
;     __device__ __forceinline__ void operator()(const f32x4 (&acc)[2][2][4][2], const Unit& u, int wr, int wc, int fr, int fq, int tid, const Pre& pre) const {
;     ...
;                 for (int bj = 0; bj < 2; ++bj) {
;                     const f32x2_t h0 = unpk_h(bw[q][mm][bj].x), h1 = unpk_h(bw[q][mm][bj].y), h2 = unpk_h(bw[q][mm][bj].z), h3 = unpk_h(bw[q][mm][bj].w);
;                     const f32x4 b0 = {h0[0], h0[1], h1[0], h1[1]}, b1 = {h2[0], h2[1], h3[0], h3[1]};
;                     const f32x4 o0 = b0 + gv[bj][0] * acc[ai][bj][m][0], o1 = b1 + gv[bj][1] * acc[ai][bj][m][1];
;                     if (nx) { ss += ((o0[0] * o0[0] + o0[1] * o0[1]) + (o0[2] * o0[2] + o0[3] * o0[3])) + ((o1[0] * o1[0] + o1[1] * o1[1]) + (o1[2] * o1[2] + o1[3] * o1[3]));
;                         u32x4 xw; xw.x = cvtpk_h(o0[0], o0[1]); xw.y = cvtpk_h(o0[2], o0[3]); xw.z = cvtpk_h(o1[0], o1[1]); xw.w = cvtpk_h(o1[2], o1[3]);
;                         __builtin_nontemporal_store(xw, (u32x4*)(xb + off + bj * HALF));
;                         const f32x4 t0 = o0 * gsn[bj][0], t1 = o1 * gsn[bj][1];
;                         u32x4 w; w.x = cvtpk(t0[0], t0[1]); w.y = cvtpk(t0[2], t0[3]); w.z = cvtpk(t1[0], t1[1]); w.w = cvtpk(t1[2], t1[3]);
;                         *(u32x4*)(XT + off + bj * HALF) = w; }
.LBB0_651:
	v_mov_b32_e32 v26, v21
	v_mov_b32_e32 v27, v17
	v_mov_b32_e32 v24, v20
	v_mov_b32_e32 v25, v16
	v_pk_mul_f32 v[26:27], v[26:27], v[26:27]
	v_mov_b32_e32 v28, v23
	v_mov_b32_e32 v29, v19
	v_pk_fma_f32 v[24:25], v[24:25], v[24:25], v[26:27]
	v_mov_b32_e32 v26, v22
	v_mov_b32_e32 v27, v18
	v_pk_mul_f32 v[28:29], v[28:29], v[28:29]
	v_pk_mul_f32 v[30:31], v[58:59], v[18:19]
	v_pk_fma_f32 v[26:27], v[26:27], v[26:27], v[28:29]
	v_cvt_pk_f16_f32 v28, v16, v17
	v_pk_add_f32 v[24:25], v[24:25], v[26:27]
	v_cvt_pk_f16_f32 v26, v20, v21
	v_cvt_pk_f16_f32 v27, v22, v23
	v_cvt_pk_f16_f32 v29, v18, v19
	v_add_f32_e32 v24, v24, v25
	global_store_dwordx4 v[34:35], v[26:29], off offset:256
	v_pk_mul_f32 v[34:35], v[56:57], v[16:17]
	v_add_f32_e32 v24, v24, v38
	v_pk_mul_f32 v[28:29], v[62:63], v[22:23]
	v_pk_mul_f32 v[26:27], v[60:61], v[20:21]
	s_nop 0
	v_cvt_pk_bf16_f32 v26, v26, v27
	v_cvt_pk_bf16_f32 v27, v28, v29
	v_cvt_pk_bf16_f32 v28, v34, v35
	v_cvt_pk_bf16_f32 v29, v30, v31
	global_store_dwordx4 v[32:33], v[26:29], off offset:256
	s_cbranch_execnz .LBB0_650

; __device__ __forceinline__ unsigned cvtpk(float lo, float hi) { f32x2_t v = {lo, hi}; bf16x2_t b = __builtin_convertvector(v, bf16x2_t); return __builtin_bit_cast(unsigned, b); }
; __device__ __forceinline__ unsigned cvtpk_h(float lo, float hi) { f32x2_t v = {lo, hi}; f16x2_t h = __builtin_convertvector(v, f16x2_t); return __builtin_bit_cast(unsigned, h); }
; __device__ __forceinline__ f32x2_t unpk_h(unsigned w) { return __builtin_convertvector(__builtin_bit_cast(f16x2_t, w), f32x2_t); }
;     __device__ __forceinline__ void operator()(const f32x4 (&acc)[2][2][4][2], const Unit& u, int wr, int wc, int fr, int fq, int tid, const Pre& pre) const {
;     ...
;             for (int mm = 0; mm < 2; ++mm) { const int m = (q & 1) * 2 + mm; const size_t off = (size_t)(row0 + ai * HALF + m * 16) * DM + col0; float ss = 0.f;
; #pragma unroll
;                 for (int bj = 0; bj < 2; ++bj) {
;                     const f32x2_t h0 = unpk_h(bw[q][mm][bj].x), h1 = unpk_h(bw[q][mm][bj].y), h2 = unpk_h(bw[q][mm][bj].z), h3 = unpk_h(bw[q][mm][bj].w);
;                     const f32x4 b0 = {h0[0], h0[1], h1[0], h1[1]}, b1 = {h2[0], h2[1], h3[0], h3[1]};
;                     const f32x4 o0 = b0 + gv[bj][0] * acc[ai][bj][m][0], o1 = b1 + gv[bj][1] * acc[ai][bj][m][1];
;                     if (nx) { ss += ((o0[0] * o0[0] + o0[1] * o0[1]) + (o0[2] * o0[2] + o0[3] * o0[3])) + ((o1[0] * o1[0] + o1[1] * o1[1]) + (o1[2] * o1[2] + o1[3] * o1[3]));
;                         u32x4 xw; xw.x = cvtpk_h(o0[0], o0[1]); xw.y = cvtpk_h(o0[2], o0[3]); xw.z = cvtpk_h(o1[0], o1[1]); xw.w = cvtpk_h(o1[2], o1[3]);
;                         __builtin_nontemporal_store(xw, (u32x4*)(xb + off + bj * HALF));
;                         const f32x4 t0 = o0 * gsn[bj][0], t1 = o1 * gsn[bj][1];
;                         u32x4 w; w.x = cvtpk(t0[0], t0[1]); w.y = cvtpk(t0[2], t0[3]); w.z = cvtpk(t1[0], t1[1]); w.w = cvtpk(t1[2], t1[3]);
;                         *(u32x4*)(XT + off + bj * HALF) = w; }
.LBB0_656:
	s_waitcnt vmcnt(1)
	v_cvt_f32_f16_sdwa v19, v100 dst_sel:DWORD dst_unused:UNUSED_PAD src0_sel:WORD_1
	v_cvt_f32_f16_e32 v18, v100
	v_cvt_f32_f16_sdwa v23, v101 dst_sel:DWORD dst_unused:UNUSED_PAD src0_sel:WORD_1
	v_cvt_f32_f16_e32 v22, v101
	v_cvt_f32_f16_sdwa v25, v102 dst_sel:DWORD dst_unused:UNUSED_PAD src0_sel:WORD_1
	v_cvt_f32_f16_sdwa v27, v103 dst_sel:DWORD dst_unused:UNUSED_PAD src0_sel:WORD_1
	v_cvt_f32_f16_e32 v26, v103
	v_cvt_f32_f16_e32 v24, v102
	s_waitcnt lgkmcnt(0)
	v_lshlrev_b64 v[16:17], 10, v[112:113]
	v_lshl_add_u64 v[20:21], v[16:17], 0, v[210:211]
	v_pk_fma_f32 v[14:15], v[14:15], v[94:95], v[22:23]
	v_pk_fma_f32 v[12:13], v[12:13], v[92:93], v[18:19]
	v_pk_fma_f32 v[10:11], v[10:11], v[90:91], v[26:27]
	v_pk_fma_f32 v[8:9], v[8:9], v[88:89], v[24:25]
	s_mov_b64 s[74:75], -1
	s_and_b64 vcc, exec, s[8:9]
	v_lshl_add_u64 v[18:19], v[16:17], 1, v[208:209]
	v_lshl_add_u64 v[16:17], v[20:21], 1, s[46:47]
	s_cbranch_vccnz .LBB0_658
	v_mov_b32_e32 v24, v13
	v_mov_b32_e32 v25, v9
	v_mov_b32_e32 v22, v12
	v_mov_b32_e32 v23, v8
	v_pk_mul_f32 v[24:25], v[24:25], v[24:25]
	v_mov_b32_e32 v26, v15
	v_mov_b32_e32 v27, v11
	v_pk_fma_f32 v[22:23], v[22:23], v[22:23], v[24:25]
	v_mov_b32_e32 v24, v14
	v_mov_b32_e32 v25, v10
	v_pk_mul_f32 v[26:27], v[26:27], v[26:27]
	v_pk_mul_f32 v[28:29], v[82:83], v[10:11]
	v_pk_fma_f32 v[24:25], v[24:25], v[24:25], v[26:27]
	v_cvt_pk_f16_f32 v26, v8, v9
	v_pk_add_f32 v[22:23], v[22:23], v[24:25]
	v_cvt_pk_f16_f32 v24, v12, v13
	v_cvt_pk_f16_f32 v25, v14, v15
	v_cvt_pk_f16_f32 v27, v10, v11
	global_store_dwordx4 v[18:19], v[24:27], off
	v_pk_mul_f32 v[30:31], v[80:81], v[8:9]
	v_add_f32_e32 v22, v22, v23
	v_pk_mul_f32 v[26:27], v[86:87], v[14:15]
	v_pk_mul_f32 v[24:25], v[84:85], v[12:13]
	s_mov_b64 s[74:75], 0
	v_cvt_pk_bf16_f32 v24, v24, v25
	v_cvt_pk_bf16_f32 v25, v26, v27
	v_cvt_pk_bf16_f32 v26, v30, v31
	v_cvt_pk_bf16_f32 v27, v28, v29
	global_store_dwordx4 v[16:17], v[24:27], off

; __device__ __forceinline__ unsigned cvtpk(float lo, float hi) { f32x2_t v = {lo, hi}; bf16x2_t b = __builtin_convertvector(v, bf16x2_t); return __builtin_bit_cast(unsigned, b); }
; __device__ __forceinline__ unsigned cvtpk_h(float lo, float hi) { f32x2_t v = {lo, hi}; f16x2_t h = __builtin_convertvector(v, f16x2_t); return __builtin_bit_cast(unsigned, h); }
; __device__ __forceinline__ f32x2_t unpk_h(unsigned w) { return __builtin_convertvector(__builtin_bit_cast(f16x2_t, w), f32x2_t); }
;     __device__ __forceinline__ void operator()(const f32x4 (&acc)[2][2][4][2], const Unit& u, int wr, int wc, int fr, int fq, int tid, const Pre& pre) const {
;     ...
;                 for (int bj = 0; bj < 2; ++bj) {
;                     const f32x2_t h0 = unpk_h(bw[q][mm][bj].x), h1 = unpk_h(bw[q][mm][bj].y), h2 = unpk_h(bw[q][mm][bj].z), h3 = unpk_h(bw[q][mm][bj].w);
;                     const f32x4 b0 = {h0[0], h0[1], h1[0], h1[1]}, b1 = {h2[0], h2[1], h3[0], h3[1]};
;                     const f32x4 o0 = b0 + gv[bj][0] * acc[ai][bj][m][0], o1 = b1 + gv[bj][1] * acc[ai][bj][m][1];
;                     if (nx) { ss += ((o0[0] * o0[0] + o0[1] * o0[1]) + (o0[2] * o0[2] + o0[3] * o0[3])) + ((o1[0] * o1[0] + o1[1] * o1[1]) + (o1[2] * o1[2] + o1[3] * o1[3]));
;                         u32x4 xw; xw.x = cvtpk_h(o0[0], o0[1]); xw.y = cvtpk_h(o0[2], o0[3]); xw.z = cvtpk_h(o1[0], o1[1]); xw.w = cvtpk_h(o1[2], o1[3]);
;                         __builtin_nontemporal_store(xw, (u32x4*)(xb + off + bj * HALF));
;                         const f32x4 t0 = o0 * gsn[bj][0], t1 = o1 * gsn[bj][1];
;                         u32x4 w; w.x = cvtpk(t0[0], t0[1]); w.y = cvtpk(t0[2], t0[3]); w.z = cvtpk(t1[0], t1[1]); w.w = cvtpk(t1[2], t1[3]);
;                         *(u32x4*)(XT + off + bj * HALF) = w; }
.LBB0_663:
	v_mov_b32_e32 v10, v5
	v_mov_b32_e32 v11, v1
	v_mov_b32_e32 v8, v4
	v_mov_b32_e32 v9, v0
	v_pk_mul_f32 v[10:11], v[10:11], v[10:11]
	v_mov_b32_e32 v12, v7
	v_mov_b32_e32 v13, v3
	v_pk_fma_f32 v[8:9], v[8:9], v[8:9], v[10:11]
	v_mov_b32_e32 v10, v6
	v_mov_b32_e32 v11, v2
	v_pk_mul_f32 v[12:13], v[12:13], v[12:13]
	v_pk_mul_f32 v[14:15], v[58:59], v[2:3]
	v_pk_fma_f32 v[10:11], v[10:11], v[10:11], v[12:13]
	v_cvt_pk_f16_f32 v12, v0, v1
	v_pk_add_f32 v[8:9], v[8:9], v[10:11]
	v_cvt_pk_f16_f32 v10, v4, v5
	v_cvt_pk_f16_f32 v11, v6, v7
	v_cvt_pk_f16_f32 v13, v2, v3
	v_add_f32_e32 v8, v8, v9
	global_store_dwordx4 v[18:19], v[10:13], off offset:256
	v_pk_mul_f32 v[18:19], v[56:57], v[0:1]
	v_add_f32_e32 v8, v8, v22
	v_pk_mul_f32 v[12:13], v[62:63], v[6:7]
	v_pk_mul_f32 v[10:11], v[60:61], v[4:5]
	s_nop 0
	v_cvt_pk_bf16_f32 v10, v10, v11
	v_cvt_pk_bf16_f32 v11, v12, v13
	v_cvt_pk_bf16_f32 v12, v18, v19
	v_cvt_pk_bf16_f32 v13, v14, v15
	global_store_dwordx4 v[16:17], v[10:13], off offset:256
	s_cbranch_execnz .LBB0_662
